# retention scan: L2 warm-up of the chunk after next (one dword touch per wave and chunk, 1/32 share per slice workgroup)
# speedup vs baseline: 1.0169x; 1.0169x over previous
.LBB0_388:
	s_or_b64 exec, exec, s[4:5]
	s_and_b32 s43, s42, 3
	v_cvt_f32_ubyte0_e32 v0, s43
	v_sub_f32_e32 v0, 0xc0a00000, v0
	v_cmp_gt_f32_e32 vcc, s29, v0
	s_and_b32 s4, s40, 3
	s_lshl_b32 s9, s4, 10
	v_cndmask_b32_e32 v2, 0, v222, vcc
	s_and_b32 s4, s25, -16
	v_add_f32_e32 v0, v0, v2
	s_and_b32 s0, s41, 4
	s_ashr_i32 s5, s4, 31
	v_exp_f32_e32 v2, v0
	s_lshl_b32 s0, s0, 24
	s_lshl_b64 s[4:5], s[4:5], 1
	s_and_b32 s33, s42, 7
	s_lshl_b32 s46, s42, 1
	s_and_b64 s[44:45], vcc, exec
	s_cselect_b32 s43, 0xffffffc0, 0
	s_waitcnt vmcnt(48)
	v_ldexp_f32 v4, v2, s43
	v_sub_f32_e32 v5, 1.0, v4
	v_add_f32_e32 v2, -1.0, v5
	v_sub_f32_e32 v3, v2, v5
	v_add_f32_e32 v3, 1.0, v3
	v_sub_f32_e64 v2, -v4, v2
	v_add_f32_e32 v6, v2, v3
	v_frexp_mant_f32_e32 v7, v5
	v_cvt_f64_f32_e32 v[2:3], v5
	v_frexp_exp_i32_f64_e32 v2, v[2:3]
	v_cmp_gt_f32_e32 vcc, s30, v7
	s_lshl_b32 s43, s33, 23
	s_lshl_b32 s44, s33, 24
	v_subbrev_co_u32_e32 v2, vcc, 0, v2, vcc
	v_sub_u32_e32 v3, 0, v2
	v_ldexp_f32 v5, v5, v3
	v_ldexp_f32 v3, v6, v3
	v_add_f32_e32 v6, -1.0, v5
	v_add_f32_e32 v9, 1.0, v5
	v_add_f32_e32 v7, 1.0, v6
	v_add_f32_e32 v10, -1.0, v9
	v_sub_f32_e32 v7, v5, v7
	v_sub_f32_e32 v5, v5, v10
	v_add_f32_e32 v7, v3, v7
	v_add_f32_e32 v3, v3, v5
	v_add_f32_e32 v5, v9, v3
	v_rcp_f32_e32 v10, v5
	v_add_f32_e32 v8, v6, v7
	v_sub_f32_e32 v6, v8, v6
	v_sub_f32_e32 v6, v7, v6
	v_sub_f32_e32 v7, v5, v9
	v_sub_f32_e32 v3, v3, v7
	v_mul_f32_e32 v7, v8, v10
	v_mul_f32_e32 v9, v5, v7
	v_fma_f32 v11, v7, v5, -v9
	v_fmac_f32_e32 v11, v7, v3
	v_add_f32_e32 v12, v9, v11
	v_sub_f32_e32 v13, v8, v12
	v_sub_f32_e32 v8, v8, v13
	v_sub_f32_e32 v9, v12, v9
	v_sub_f32_e32 v8, v8, v12
	v_add_f32_e32 v6, v6, v8
	v_sub_f32_e32 v8, v9, v11
	v_add_f32_e32 v6, v8, v6
	v_add_f32_e32 v8, v13, v6
	v_mul_f32_e32 v9, v10, v8
	v_mul_f32_e32 v11, v5, v9
	v_fma_f32 v5, v9, v5, -v11
	v_fmac_f32_e32 v5, v9, v3
	v_sub_f32_e32 v3, v13, v8
	v_add_f32_e32 v3, v6, v3
	v_add_f32_e32 v6, v11, v5
	v_sub_f32_e32 v12, v8, v6
	v_sub_f32_e32 v8, v8, v12
	v_sub_f32_e32 v11, v6, v11
	v_sub_f32_e32 v6, v8, v6
	v_add_f32_e32 v3, v3, v6
	v_sub_f32_e32 v5, v11, v5
	v_cvt_f32_i32_e32 v2, v2
	v_add_f32_e32 v3, v5, v3
	v_add_f32_e32 v5, v7, v9
	v_add_f32_e32 v3, v12, v3
	v_sub_f32_e32 v6, v5, v7
	v_mul_f32_e32 v3, v10, v3
	v_sub_f32_e32 v6, v9, v6
	v_add_f32_e32 v3, v6, v3
	v_mul_f32_e32 v9, 0x3f317218, v2
	v_add_f32_e32 v6, v5, v3
	v_fma_f32 v10, v2, s31, -v9
	v_mul_f32_e32 v7, v6, v6
	v_fmac_f32_e32 v10, 0xb102e308, v2
	v_sub_f32_e32 v2, v6, v5
	v_fmamk_f32 v8, v7, 0x3e9b6dac, v223
	v_sub_f32_e32 v2, v3, v2
	v_add_f32_e32 v3, v9, v10
	v_fmaak_f32 v8, v7, v8, 0x3f2aaada
	v_sub_f32_e32 v5, v3, v9
	v_ldexp_f32 v9, v6, 1
	v_mul_f32_e32 v6, v6, v7
	v_mul_f32_e32 v6, v6, v8
	v_add_f32_e32 v7, v9, v6
	v_sub_f32_e32 v8, v7, v9
	v_ldexp_f32 v2, v2, 1
	v_sub_f32_e32 v6, v6, v8
	v_add_f32_e32 v2, v2, v6
	v_add_f32_e32 v6, v7, v2
	v_sub_f32_e32 v7, v6, v7
	v_sub_f32_e32 v2, v2, v7
	v_add_f32_e32 v7, v3, v6
	v_sub_f32_e32 v8, v7, v3
	v_sub_f32_e32 v9, v7, v8
	v_sub_f32_e32 v5, v10, v5
	v_sub_f32_e32 v3, v3, v9
	v_sub_f32_e32 v6, v6, v8
	v_add_f32_e32 v3, v6, v3
	v_add_f32_e32 v6, v5, v2
	v_sub_f32_e32 v8, v6, v5
	v_sub_f32_e32 v9, v6, v8
	v_sub_f32_e32 v5, v5, v9
	v_sub_f32_e32 v2, v2, v8
	v_add_f32_e32 v3, v6, v3
	v_add_f32_e32 v2, v2, v5
	v_add_f32_e32 v5, v7, v3
	v_sub_f32_e32 v6, v5, v7
	v_sub_f32_e32 v3, v3, v6
	v_add_f32_e32 v2, v2, v3
	v_add_f32_e32 v2, v5, v2
	v_cmp_nlt_f32_e32 vcc, 1.0, v4
	s_add_u32 s44, s15, s44
	s_addc_u32 s45, s16, 0
	v_cndmask_b32_e32 v2, v224, v2, vcc
	v_cmp_neq_f32_e32 vcc, 1.0, v4
	s_lshl_b32 s33, s33, 22
	v_and_b32_e32 v181, 15, v1
	v_cndmask_b32_e32 v2, v225, v2, vcc
	v_cmp_gt_f32_e32 vcc, s34, v4
	v_bfe_u32 v182, v1, 4, 2
	v_lshlrev_b32_e32 v192, 4, v182
	v_lshlrev_b32_e32 v255, 8, v182
	v_lshl_or_b32 v255, v181, 4, v255
	v_cndmask_b32_e64 v183, v2, -v4, vcc
	v_mul_f32_e32 v2, 0x43000000, v183
	v_mul_f32_e32 v2, 0x3fb8aa3b, v2
	v_exp_f32_e32 v194, v2
	s_and_b32 s100, s46, -16
	s_lshl_b32 s100, s100, 8
	v_add_u32_e32 v2, s100, v255
	v_mov_b32_e32 v3, 0
	v_lshl_add_u64 v[2:3], s[44:45], 0, v[2:3]
	s_add_u32 s44, s17, s43
	s_addc_u32 s45, s22, 0
	s_add_u32 s46, s3, s43
	v_ashrrev_i32_e32 v4, 1, v1
	s_addc_u32 s47, s14, 0
	s_waitcnt vmcnt(44)
	v_and_b32_e32 v20, 0xffffffe0, v4
	s_add_u32 s48, s23, s33
	s_addc_u32 s49, s24, 0
	v_ashrrev_i32_e32 v199, 31, v20
	v_or_b32_e32 v198, v20, v181
	v_lshl_or_b32 v180, v182, 2, v20
	v_mov_b64_e32 v[196:197], v[2:3]
	v_mov_b32_e32 v2, v255
	v_mov_b32_e32 v3, 0
	v_lshl_add_u64 v[200:201], s[48:49], 0, v[2:3]
	v_and_b32_e32 v2, -16, v198
	v_mov_b32_e32 v3, 0
	v_lshlrev_b64 v[2:3], 8, v[2:3]
	v_or_b32_e32 v4, 1, v180
	v_lshl_add_u64 v[2:3], v[200:201], 0, v[2:3]
	s_waitcnt vmcnt(36)
	v_ashrrev_i32_e32 v25, 31, v198
	v_and_b32_e32 v24, -16, v198
	s_waitcnt lgkmcnt(0)
	s_barrier
	v_cvt_f32_i32_e32 v184, v4
	global_load_dwordx4 v[16:19], v[196:197], off
	global_load_dwordx4 v[12:15], v[196:197], off offset:1024
	global_load_dwordx4 v[8:11], v[196:197], off offset:2048
	global_load_dwordx4 v[4:7], v[196:197], off offset:3072
	v_add_u32_e32 v202, 0x1000, v255
	v_mov_b32_e32 v203, s45
	v_add_co_u32_e32 v202, vcc, s44, v202
	s_nop 1
	v_addc_co_u32_e32 v203, vcc, 0, v203, vcc
	global_load_dwordx4 v[136:139], v[2:3], off
	global_load_dwordx4 v[52:55], v[2:3], off offset:1024
	global_load_dwordx4 v[32:35], v[2:3], off offset:2048
	global_load_dwordx4 v[20:23], v[2:3], off offset:3072
	v_lshlrev_b64 v[24:25], 9, v[24:25]
	v_add_co_u32_e32 v2, vcc, s35, v2
	v_lshl_add_u64 v[24:25], v[202:203], 0, v[24:25]
	s_nop 0
	v_addc_co_u32_e32 v3, vcc, 0, v3, vcc
	global_load_dwordx4 v[60:63], v[24:25], off offset:-4096
	global_load_dwordx4 v[56:59], v[24:25], off offset:-3072
	global_load_dwordx4 v[48:51], v[24:25], off offset:-2048
	global_load_dwordx4 v[44:47], v[24:25], off offset:-1024
	global_load_dwordx4 v[40:43], v[24:25], off
	global_load_dwordx4 v[36:39], v[24:25], off offset:1024
	global_load_dwordx4 v[28:31], v[24:25], off offset:2048
	s_nop 0
	global_load_dwordx4 v[24:27], v[24:25], off offset:3072
	s_nop 0
	global_load_dwordx4 v[164:167], v[2:3], off
	global_load_dwordx4 v[92:95], v[2:3], off offset:1024
	global_load_dwordx4 v[68:71], v[2:3], off offset:2048
	global_load_dwordx4 v[64:67], v[2:3], off offset:3072
	v_and_b32_e32 v2, -16, v198
	v_or_b32_e32 v2, 16, v2
	v_ashrrev_i32_e32 v3, 31, v2
	s_waitcnt vmcnt(28)
	v_lshlrev_b32_e32 v144, 7, v1
	v_lshlrev_b64 v[2:3], 9, v[2:3]
	v_and_b32_e32 v206, 0xffffe000, v144
	v_lshl_add_u64 v[2:3], v[202:203], 0, v[2:3]
	v_mov_b32_e32 v205, s47
	v_add_co_u32_e32 v204, vcc, s46, v255
	s_nop 1
	v_addc_co_u32_e32 v205, vcc, 0, v205, vcc
	v_ashrrev_i32_e32 v207, 31, v206
	v_or_b32_e32 v208, 0x800, v206
	global_load_dwordx4 v[104:107], v[2:3], off offset:-4096
	global_load_dwordx4 v[100:103], v[2:3], off offset:-3072
	global_load_dwordx4 v[96:99], v[2:3], off offset:-2048
	global_load_dwordx4 v[88:91], v[2:3], off offset:-1024
	global_load_dwordx4 v[84:87], v[2:3], off
	global_load_dwordx4 v[80:83], v[2:3], off offset:1024
	global_load_dwordx4 v[76:79], v[2:3], off offset:2048
	global_load_dwordx4 v[72:75], v[2:3], off offset:3072
	v_lshl_add_u64 v[2:3], v[206:207], 1, v[204:205]
	v_ashrrev_i32_e32 v209, 31, v208
	v_or_b32_e32 v210, 0x1000, v206
	global_load_dwordx4 v[176:179], v[2:3], off
	global_load_dwordx4 v[120:123], v[2:3], off offset:1024
	global_load_dwordx4 v[112:115], v[2:3], off offset:2048
	global_load_dwordx4 v[108:111], v[2:3], off offset:3072
	v_lshl_add_u64 v[2:3], v[208:209], 1, v[204:205]
	v_ashrrev_i32_e32 v211, 31, v210
	v_or_b32_e32 v212, 0x1800, v206
	global_load_dwordx4 v[172:175], v[2:3], off
	global_load_dwordx4 v[132:135], v[2:3], off offset:1024
	global_load_dwordx4 v[124:127], v[2:3], off offset:2048
	global_load_dwordx4 v[116:119], v[2:3], off offset:3072
	v_lshl_add_u64 v[2:3], v[210:211], 1, v[204:205]
	v_ashrrev_i32_e32 v213, 31, v212
	global_load_dwordx4 v[168:171], v[2:3], off
	global_load_dwordx4 v[148:151], v[2:3], off offset:1024
	global_load_dwordx4 v[140:143], v[2:3], off offset:2048
	global_load_dwordx4 v[128:131], v[2:3], off offset:3072
	v_lshl_add_u64 v[2:3], v[212:213], 1, v[204:205]
	global_load_dwordx4 v[160:163], v[2:3], off
	global_load_dwordx4 v[156:159], v[2:3], off offset:1024
	global_load_dwordx4 v[152:155], v[2:3], off offset:2048
	global_load_dwordx4 v[144:147], v[2:3], off offset:3072
	v_or_b32_e32 v2, 2, v180
	v_cvt_f32_i32_e32 v2, v2
	v_mul_f32_e32 v3, v183, v184
	v_mul_f32_e32 v3, 0x3fb8aa3b, v3
	v_exp_f32_e32 v227, v3
	v_mul_f32_e32 v2, v183, v2
	v_mul_f32_e32 v2, 0x3fb8aa3b, v2
	v_exp_f32_e32 v228, v2
	v_add_u32_e32 v2, 4, v180
	v_or_b32_e32 v3, 3, v180
	v_cvt_f32_i32_e32 v2, v2
	v_cvt_f32_i32_e32 v3, v3
	s_add_u32 s4, s4, s9
	s_addc_u32 s5, s5, 0
	v_mul_f32_e32 v2, v183, v2
	v_mul_f32_e32 v3, v183, v3
	v_mul_f32_e32 v2, 0x3fb8aa3b, v2
	v_mul_f32_e32 v3, 0x3fb8aa3b, v3
	v_exp_f32_e32 v230, v2
	v_or_b32_e32 v2, 18, v180
	v_exp_f32_e32 v229, v3
	v_or_b32_e32 v3, 17, v180
	v_cvt_f32_i32_e32 v2, v2
	v_cvt_f32_i32_e32 v3, v3
	s_add_u32 s4, s4, s0
	v_and_b32_e32 v1, 0x7fffffc0, v1
	v_mul_f32_e32 v2, v183, v2
	v_mul_f32_e32 v3, v183, v3
	v_mul_f32_e32 v2, 0x3fb8aa3b, v2
	v_mul_f32_e32 v3, 0x3fb8aa3b, v3
	v_exp_f32_e32 v232, v2
	v_add_u32_e32 v2, 20, v180
	v_exp_f32_e32 v231, v3
	v_or_b32_e32 v3, 19, v180
	v_cvt_f32_i32_e32 v2, v2
	v_cvt_f32_i32_e32 v3, v3
	s_addc_u32 s5, s5, 0
	v_lshlrev_b32_e32 v1, 1, v1
	v_mul_f32_e32 v2, v183, v2
	v_mul_f32_e32 v3, v183, v3
	v_mul_f32_e32 v2, 0x3fb8aa3b, v2
	v_mul_f32_e32 v3, 0x3fb8aa3b, v3
	v_exp_f32_e32 v234, v2
	v_or_b32_e32 v2, 16, v180
	v_exp_f32_e32 v233, v3
	v_ashrrev_i32_e32 v3, 31, v2
	v_lshlrev_b64 v[2:3], 12, v[2:3]
	v_lshl_add_u64 v[2:3], s[4:5], 0, v[2:3]
	v_lshlrev_b32_e32 v184, 1, v181
	v_mul_u32_u24_e32 v183, 0x210, v181
	v_mad_u32_u24 v1, v181, s36, v1
	v_or_b32_e32 v2, v2, v184
	v_ashrrev_i32_e32 v181, 31, v180
	v_lshl_add_u64 v[216:217], s[70:71], 0, v[2:3]
	v_lshlrev_b64 v[2:3], 12, v[180:181]
	v_lshl_add_u64 v[2:3], s[4:5], 0, v[2:3]
	v_mov_b32_e32 v0, 0
	v_lshlrev_b32_e32 v182, 3, v182
	v_or_b32_e32 v2, v2, v184
	s_mov_b32 s8, 1
	v_mov_b32_e32 v214, v194
	v_mov_b32_e32 v215, v194
	v_lshl_add_u64 v[218:219], s[70:71], 0, v[2:3]
	s_mov_b64 s[4:5], 0
	v_add_u32_e32 v192, v183, v192
	v_add_u32_e32 v235, v1, v182
	v_mov_b32_e32 v1, v0
	v_mov_b32_e32 v2, v0
	v_mov_b32_e32 v3, v0
	v_mov_b32_e32 v188, v0
	v_mov_b32_e32 v189, v0
	v_mov_b32_e32 v190, v0
	v_mov_b32_e32 v191, v0
	v_mov_b32_e32 v184, v0
	v_mov_b32_e32 v185, v0
	v_mov_b32_e32 v186, v0
	v_mov_b32_e32 v187, v0
	v_mov_b32_e32 v180, v0
	v_mov_b32_e32 v181, v0
	v_mov_b32_e32 v182, v0
	v_mov_b32_e32 v183, v0
	v_lshrrev_b32_e32 v193, 6, v220
	v_sub_co_u32_e32 v222, vcc, v196, v255
	v_subbrev_co_u32_e32 v223, vcc, 0, v197, vcc
	v_readfirstlane_b32 s50, v193
	v_readfirstlane_b32 s54, v222
	v_readfirstlane_b32 s55, v223
	s_lshr_b32 s51, s42, 3
	s_lshl_b32 s53, s51, 11
	s_add_u32 s78, s44, s53
	s_addc_u32 s79, s45, 0
	s_mov_b32 s52, 0x10000
	s_mov_b32 s80, 15
	s_cmp_eq_u32 s50, 1
	s_cbranch_scc0 .Lscn_t1
	s_add_u32 s78, s46, s53
	s_addc_u32 s79, s47, 0
.Lscn_t1:
	s_cmp_eq_u32 s50, 2
	s_cbranch_scc0 .Lscn_t2
	s_lshl_b32 s53, s51, 10
	s_add_u32 s78, s48, s53
	s_addc_u32 s79, s49, 0
	s_mov_b32 s52, 0x8000
	s_mov_b32 s80, 7
.Lscn_t2:
	s_cmp_eq_u32 s50, 3
	s_cbranch_scc0 .Lscn_t3
	s_mov_b64 s[78:79], s[54:55]
	s_mov_b32 s52, 0x20000
	s_mov_b32 s80, 31
.Lscn_t3:
	s_lshl_b32 s53, s52, 1
	s_add_u32 s78, s78, s53
	s_addc_u32 s79, s79, 0
	v_and_b32_e32 v193, s80, v220
	v_lshlrev_b32_e32 v193, 7, v193
	v_mov_b32_e32 v223, s79
	v_add_co_u32_e32 v222, vcc, s78, v193
	v_addc_co_u32_e32 v223, vcc, 0, v223, vcc
	global_load_dword v225, v[222:223], off
.LBB0_389:
	v_mov_b32_e32 v195, v194
	s_waitcnt vmcnt(40)
	v_mfma_f32_16x16x32_bf16 v[136:139], v[136:139], v[16:19], 0
	v_mul_f32_e64 v0, v214, v0
	v_mul_f32_e64 v1, v215, v1
	v_pk_mul_f32 v[2:3], v[194:195], v[2:3]
	s_waitcnt vmcnt(28)
	v_mfma_f32_16x16x32_bf16 v[164:167], v[164:167], v[16:19], 0
	s_waitcnt vmcnt(16)
	v_mfma_f32_16x16x32_bf16 v[0:3], v[176:179], v[16:19], v[0:3]
	v_mul_f32_e64 v176, v214, v188
	v_mul_f32_e64 v177, v215, v189
	v_pk_mul_f32 v[178:179], v[194:195], v[190:191]
	v_mfma_f32_16x16x32_bf16 v[52:55], v[52:55], v[12:15], v[136:139]
	s_waitcnt vmcnt(12)
	v_mfma_f32_16x16x32_bf16 v[172:175], v[172:175], v[16:19], v[176:179]
	s_nop 2
	v_mul_f32_e64 v176, v214, v184
	v_mul_f32_e64 v177, v215, v185
	v_pk_mul_f32 v[178:179], v[194:195], v[186:187]
	v_mfma_f32_16x16x32_bf16 v[92:95], v[92:95], v[12:15], v[164:167]
	s_waitcnt vmcnt(8)
	v_mfma_f32_16x16x32_bf16 v[168:171], v[168:171], v[16:19], v[176:179]
	s_nop 2
	v_mul_f32_e64 v176, v214, v180
	v_mul_f32_e64 v177, v215, v181
	v_pk_mul_f32 v[178:179], v[194:195], v[182:183]
	v_mfma_f32_16x16x32_bf16 v[0:3], v[120:123], v[12:15], v[0:3]
	s_waitcnt vmcnt(4)
	v_mfma_f32_16x16x32_bf16 v[16:19], v[160:163], v[16:19], v[176:179]
	ds_read_b128 v[136:139], v192
	ds_read_b128 v[160:163], v192 offset:64
	s_waitcnt lgkmcnt(1)
	v_mfma_f32_16x16x32_bf16 v[60:63], v[60:63], v[136:139], 0
	v_mfma_f32_16x16x32_bf16 v[104:107], v[104:107], v[136:139], 0
	v_mfma_f32_16x16x32_bf16 v[120:123], v[132:135], v[12:15], v[172:175]
	v_mfma_f32_16x16x32_bf16 v[132:135], v[148:151], v[12:15], v[168:171]
	s_waitcnt vmcnt(3)
	v_mfma_f32_16x16x32_bf16 v[12:15], v[156:159], v[12:15], v[16:19]
	v_mfma_f32_16x16x32_bf16 v[16:19], v[32:35], v[8:11], v[52:55]
	v_mfma_f32_16x16x32_bf16 v[32:35], v[68:71], v[8:11], v[92:95]
	s_waitcnt lgkmcnt(0)
	v_mfma_f32_16x16x32_bf16 v[52:55], v[56:59], v[160:163], v[60:63]
	v_mfma_f32_16x16x32_bf16 v[56:59], v[100:103], v[160:163], v[104:107]
	v_mfma_f32_16x16x32_bf16 v[0:3], v[112:115], v[8:11], v[0:3]
	v_mfma_f32_16x16x32_bf16 v[60:63], v[124:127], v[8:11], v[120:123]
	v_mfma_f32_16x16x32_bf16 v[68:71], v[140:143], v[8:11], v[132:135]
	s_waitcnt vmcnt(2)
	v_mfma_f32_16x16x32_bf16 v[8:11], v[152:155], v[8:11], v[12:15]
	v_mfma_f32_16x16x32_bf16 v[236:239], v[20:23], v[4:7], v[16:19]
	s_nop 1
	ds_read_b128 v[12:15], v192 offset:128
	ds_read_b128 v[16:19], v192 offset:192
	s_waitcnt lgkmcnt(1)
	v_mfma_f32_16x16x32_bf16 v[20:23], v[48:51], v[12:15], v[52:55]
	v_mfma_f32_16x16x32_bf16 v[12:15], v[96:99], v[12:15], v[56:59]
	v_mfma_f32_16x16x32_bf16 v[240:243], v[64:67], v[4:7], v[32:35]
	v_mfma_f32_16x16x32_bf16 v[0:3], v[108:111], v[4:7], v[0:3]
	v_mfma_f32_16x16x32_bf16 v[188:191], v[116:119], v[4:7], v[60:63]
	v_mfma_f32_16x16x32_bf16 v[184:187], v[128:131], v[4:7], v[68:71]
	s_waitcnt vmcnt(1)
	v_mfma_f32_16x16x32_bf16 v[180:183], v[144:147], v[4:7], v[8:11]
	s_waitcnt lgkmcnt(0)
	v_mfma_f32_16x16x32_bf16 v[4:7], v[44:47], v[16:19], v[20:23]
	v_mfma_f32_16x16x32_bf16 v[8:11], v[88:91], v[16:19], v[12:15]
	s_nop 2
	ds_read_b128 v[12:15], v192 offset:256
	ds_read_b128 v[16:19], v192 offset:320
	s_waitcnt lgkmcnt(1)
	v_mfma_f32_16x16x32_bf16 v[4:7], v[40:43], v[12:15], v[4:7]
	v_mfma_f32_16x16x32_bf16 v[8:11], v[84:87], v[12:15], v[8:11]
	s_waitcnt lgkmcnt(0)
	v_mfma_f32_16x16x32_bf16 v[4:7], v[36:39], v[16:19], v[4:7]
	v_mfma_f32_16x16x32_bf16 v[8:11], v[80:83], v[16:19], v[8:11]
	ds_read_b128 v[12:15], v192 offset:384
	ds_read_b128 v[16:19], v192 offset:448
	s_waitcnt lgkmcnt(1)
	v_mfma_f32_16x16x32_bf16 v[4:7], v[28:31], v[12:15], v[4:7]
	v_mfma_f32_16x16x32_bf16 v[8:11], v[76:79], v[12:15], v[8:11]
	s_waitcnt lgkmcnt(0)
	v_mfma_f32_16x16x32_bf16 v[244:247], v[24:27], v[16:19], v[4:7]
	v_mfma_f32_16x16x32_bf16 v[248:251], v[72:75], v[16:19], v[8:11]
	s_min_i32 s9, s8, 0x7f
	s_lshl_b32 s0, s9, 17
	s_nop 1
	v_lshl_add_u64 v[4:5], v[196:197], 0, s[0:1]
	s_lshl_b32 s0, s9, 7
	v_and_b32_e32 v72, -16, v198
	v_add_u32_e32 v72, s0, v72
	v_and_b32_e32 v20, -16, v198
	v_mov_b32_e32 v21, 0
	v_lshl_add_u64 v[20:21], v[20:21], 0, s[0:1]
	v_ashrrev_i32_e32 v73, 31, v72
	v_lshlrev_b64 v[20:21], 8, v[20:21]
	v_lshlrev_b64 v[24:25], 9, v[72:73]
	v_or_b32_e32 v72, 16, v72
	v_lshl_add_u64 v[64:65], v[200:201], 0, v[20:21]
	v_ashrrev_i32_e32 v73, 31, v72
	global_load_dwordx4 v[16:19], v[4:5], off
	global_load_dwordx4 v[12:15], v[4:5], off offset:1024
	global_load_dwordx4 v[8:11], v[4:5], off offset:2048
	s_nop 0
	global_load_dwordx4 v[4:7], v[4:5], off offset:3072
	s_nop 0
	global_load_dwordx4 v[136:139], v[64:65], off
	global_load_dwordx4 v[52:55], v[64:65], off offset:1024
	global_load_dwordx4 v[32:35], v[64:65], off offset:2048
	global_load_dwordx4 v[20:23], v[64:65], off offset:3072
	v_add_co_u32_e32 v64, vcc, s35, v64
	v_lshlrev_b64 v[72:73], 9, v[72:73]
	v_lshl_add_u64 v[24:25], v[202:203], 0, v[24:25]
	v_addc_co_u32_e32 v65, vcc, 0, v65, vcc
	v_lshl_add_u64 v[72:73], v[202:203], 0, v[72:73]
	global_load_dwordx4 v[60:63], v[24:25], off offset:-4096
	global_load_dwordx4 v[56:59], v[24:25], off offset:-3072
	global_load_dwordx4 v[48:51], v[24:25], off offset:-2048
	global_load_dwordx4 v[44:47], v[24:25], off offset:-1024
	global_load_dwordx4 v[40:43], v[24:25], off
	global_load_dwordx4 v[36:39], v[24:25], off offset:1024
	global_load_dwordx4 v[28:31], v[24:25], off offset:2048
	s_nop 0
	global_load_dwordx4 v[24:27], v[24:25], off offset:3072
	s_nop 0
	global_load_dwordx4 v[164:167], v[64:65], off
	global_load_dwordx4 v[92:95], v[64:65], off offset:1024
	global_load_dwordx4 v[68:71], v[64:65], off offset:2048
	s_nop 0
	global_load_dwordx4 v[64:67], v[64:65], off offset:3072
	s_nop 0
	global_load_dwordx4 v[104:107], v[72:73], off offset:-4096
	global_load_dwordx4 v[100:103], v[72:73], off offset:-3072
	global_load_dwordx4 v[96:99], v[72:73], off offset:-2048
	global_load_dwordx4 v[88:91], v[72:73], off offset:-1024
	global_load_dwordx4 v[84:87], v[72:73], off
	global_load_dwordx4 v[80:83], v[72:73], off offset:1024
	global_load_dwordx4 v[76:79], v[72:73], off offset:2048
	s_nop 0
	global_load_dwordx4 v[72:75], v[72:73], off offset:3072
	s_lshl_b32 s0, s9, 16
	v_lshl_add_u64 v[144:145], v[204:205], 0, s[0:1]
	v_lshl_add_u64 v[108:109], v[206:207], 1, v[144:145]
	v_lshl_add_u64 v[116:117], v[208:209], 1, v[144:145]
	v_lshl_add_u64 v[128:129], v[210:211], 1, v[144:145]
	v_lshl_add_u64 v[144:145], v[212:213], 1, v[144:145]
	global_load_dwordx4 v[176:179], v[108:109], off
	global_load_dwordx4 v[120:123], v[108:109], off offset:1024
	global_load_dwordx4 v[112:115], v[108:109], off offset:2048
	s_nop 0
	global_load_dwordx4 v[108:111], v[108:109], off offset:3072
	s_nop 0
	global_load_dwordx4 v[172:175], v[116:117], off
	global_load_dwordx4 v[132:135], v[116:117], off offset:1024
	global_load_dwordx4 v[124:127], v[116:117], off offset:2048
	s_nop 0
	global_load_dwordx4 v[116:119], v[116:117], off offset:3072
	s_nop 0
	global_load_dwordx4 v[168:171], v[128:129], off
	global_load_dwordx4 v[148:151], v[128:129], off offset:1024
	global_load_dwordx4 v[140:143], v[128:129], off offset:2048
	s_nop 0
	global_load_dwordx4 v[128:131], v[128:129], off offset:3072
	s_nop 0
	global_load_dwordx4 v[160:163], v[144:145], off
	global_load_dwordx4 v[156:159], v[144:145], off offset:1024
	global_load_dwordx4 v[152:155], v[144:145], off offset:2048
	s_nop 0
	global_load_dwordx4 v[144:147], v[144:145], off offset:3072
	v_add_co_u32_e32 v222, vcc, s52, v222
	v_addc_co_u32_e32 v223, vcc, 0, v223, vcc
	global_load_dword v225, v[222:223], off
	v_fma_f32 v195, v227, v244, v236
	v_bfe_u32 v236, v195, 16, 1
	v_add3_u32 v195, v195, v236, s37
	v_lshl_add_u64 v[252:253], v[218:219], 0, s[4:5]
	global_store_short_d16_hi v[252:253], v195, off
	v_fma_f32 v195, v228, v245, v237
	v_bfe_u32 v236, v195, 16, 1
	v_add3_u32 v195, v195, v236, s37
	v_add_co_u32_e32 v236, vcc, s38, v252
	v_fmac_f32_e32 v239, v230, v247
	s_nop 0
	v_addc_co_u32_e32 v237, vcc, 0, v253, vcc
	global_store_short_d16_hi v[236:237], v195, off offset:-4096
	v_fma_f32 v195, v229, v246, v238
	v_bfe_u32 v238, v195, 16, 1
	v_add3_u32 v195, v195, v238, s37
	global_store_short_d16_hi v[236:237], v195, off
	v_bfe_u32 v195, v239, 16, 1
	v_add_co_u32_e32 v236, vcc, s39, v252
	v_add3_u32 v195, v239, v195, s37
	s_nop 0
	v_addc_co_u32_e32 v237, vcc, 0, v253, vcc
	global_store_short_d16_hi v[236:237], v195, off
	v_fma_f32 v195, v231, v248, v240
	v_bfe_u32 v236, v195, 16, 1
	v_add3_u32 v195, v195, v236, s37
	v_lshl_add_u64 v[236:237], v[216:217], 0, s[4:5]
	global_store_short_d16_hi v[236:237], v195, off
	v_fma_f32 v195, v232, v249, v241
	v_bfe_u32 v238, v195, 16, 1
	v_add3_u32 v195, v195, v238, s37
	v_add_co_u32_e32 v238, vcc, s38, v236
	v_fmac_f32_e32 v243, v234, v251
	s_nop 0
	v_addc_co_u32_e32 v239, vcc, 0, v237, vcc
	global_store_short_d16_hi v[238:239], v195, off offset:-4096
	v_fma_f32 v195, v233, v250, v242
	v_bfe_u32 v240, v195, 16, 1
	v_add3_u32 v195, v195, v240, s37
	global_store_short_d16_hi v[238:239], v195, off
	v_bfe_u32 v195, v243, 16, 1
	v_add_co_u32_e32 v236, vcc, s39, v236
	v_add3_u32 v195, v243, v195, s37
	s_nop 0
	v_addc_co_u32_e32 v237, vcc, 0, v237, vcc
	global_store_short_d16_hi v[236:237], v195, off
	v_and_b32_sdwa v237, v3, v226 dst_sel:DWORD dst_unused:UNUSED_PAD src0_sel:WORD_1 src1_sel:DWORD
	v_and_b32_sdwa v238, v1, v226 dst_sel:DWORD dst_unused:UNUSED_PAD src0_sel:WORD_1 src1_sel:DWORD
	v_and_b32_sdwa v195, v2, v226 dst_sel:DWORD dst_unused:UNUSED_PAD src0_sel:WORD_1 src1_sel:DWORD
	v_and_b32_sdwa v236, v0, v226 dst_sel:DWORD dst_unused:UNUSED_PAD src0_sel:WORD_1 src1_sel:DWORD
	v_add3_u32 v237, v3, v237, s37
	v_add3_u32 v238, v1, v238, s37
	v_add3_u32 v236, v0, v236, s37
	v_add3_u32 v195, v2, v195, s37
	v_and_b32_e32 v237, 0xffff0000, v237
	v_and_b32_e32 v238, 0xffff0000, v238
	v_and_b32_sdwa v239, v191, v226 dst_sel:DWORD dst_unused:UNUSED_PAD src0_sel:WORD_1 src1_sel:DWORD
	v_and_b32_sdwa v240, v189, v226 dst_sel:DWORD dst_unused:UNUSED_PAD src0_sel:WORD_1 src1_sel:DWORD
	v_or_b32_sdwa v237, v237, v195 dst_sel:DWORD dst_unused:UNUSED_PAD src0_sel:DWORD src1_sel:WORD_1
	v_or_b32_sdwa v236, v238, v236 dst_sel:DWORD dst_unused:UNUSED_PAD src0_sel:DWORD src1_sel:WORD_1
	v_and_b32_sdwa v195, v190, v226 dst_sel:DWORD dst_unused:UNUSED_PAD src0_sel:WORD_1 src1_sel:DWORD
	v_and_b32_sdwa v238, v188, v226 dst_sel:DWORD dst_unused:UNUSED_PAD src0_sel:WORD_1 src1_sel:DWORD
	v_add3_u32 v239, v191, v239, s37
	v_add3_u32 v240, v189, v240, s37
	v_add3_u32 v238, v188, v238, s37
	v_add3_u32 v195, v190, v195, s37
	v_and_b32_e32 v239, 0xffff0000, v239
	v_and_b32_e32 v240, 0xffff0000, v240
	v_or_b32_sdwa v239, v239, v195 dst_sel:DWORD dst_unused:UNUSED_PAD src0_sel:DWORD src1_sel:WORD_1
	v_or_b32_sdwa v238, v240, v238 dst_sel:DWORD dst_unused:UNUSED_PAD src0_sel:DWORD src1_sel:WORD_1
	s_waitcnt lgkmcnt(0)
	s_barrier
	ds_write2_b64 v235, v[236:237], v[238:239] offset1:4
	v_and_b32_sdwa v237, v187, v226 dst_sel:DWORD dst_unused:UNUSED_PAD src0_sel:WORD_1 src1_sel:DWORD
	v_and_b32_sdwa v238, v185, v226 dst_sel:DWORD dst_unused:UNUSED_PAD src0_sel:WORD_1 src1_sel:DWORD
	v_and_b32_sdwa v195, v186, v226 dst_sel:DWORD dst_unused:UNUSED_PAD src0_sel:WORD_1 src1_sel:DWORD
	v_and_b32_sdwa v236, v184, v226 dst_sel:DWORD dst_unused:UNUSED_PAD src0_sel:WORD_1 src1_sel:DWORD
	v_add3_u32 v237, v187, v237, s37
	v_add3_u32 v238, v185, v238, s37
	v_add3_u32 v236, v184, v236, s37
	v_add3_u32 v195, v186, v195, s37
	v_and_b32_e32 v237, 0xffff0000, v237
	v_and_b32_e32 v238, 0xffff0000, v238
	v_and_b32_sdwa v239, v183, v226 dst_sel:DWORD dst_unused:UNUSED_PAD src0_sel:WORD_1 src1_sel:DWORD
	v_and_b32_sdwa v240, v181, v226 dst_sel:DWORD dst_unused:UNUSED_PAD src0_sel:WORD_1 src1_sel:DWORD
	v_or_b32_sdwa v237, v237, v195 dst_sel:DWORD dst_unused:UNUSED_PAD src0_sel:DWORD src1_sel:WORD_1
	v_or_b32_sdwa v236, v238, v236 dst_sel:DWORD dst_unused:UNUSED_PAD src0_sel:DWORD src1_sel:WORD_1
	v_and_b32_sdwa v195, v182, v226 dst_sel:DWORD dst_unused:UNUSED_PAD src0_sel:WORD_1 src1_sel:DWORD
	v_and_b32_sdwa v238, v180, v226 dst_sel:DWORD dst_unused:UNUSED_PAD src0_sel:WORD_1 src1_sel:DWORD
	v_add3_u32 v239, v183, v239, s37
	v_add3_u32 v240, v181, v240, s37
	v_add3_u32 v238, v180, v238, s37
	v_add3_u32 v195, v182, v195, s37
	v_and_b32_e32 v239, 0xffff0000, v239
	v_and_b32_e32 v240, 0xffff0000, v240
	v_or_b32_sdwa v239, v239, v195 dst_sel:DWORD dst_unused:UNUSED_PAD src0_sel:DWORD src1_sel:WORD_1
	v_or_b32_sdwa v238, v240, v238 dst_sel:DWORD dst_unused:UNUSED_PAD src0_sel:DWORD src1_sel:WORD_1
	ds_write2_b64 v235, v[236:237], v[238:239] offset0:8 offset1:12
	s_waitcnt lgkmcnt(0)
	s_barrier
	s_add_u32 s4, s4, 0x80000
	s_addc_u32 s5, s5, 0
	s_add_i32 s8, s8, 1
	s_cmp_lg_u32 s4, 0x4000000
	s_cbranch_scc1 .LBB0_389
	s_add_i32 s42, s42, s74
	s_add_i32 s41, s41, s74
	s_add_i32 s40, s40, s74
	s_add_i32 s25, s25, s26
	s_cmpk_lt_i32 s42, 0x100
	s_cbranch_scc1 .LBB0_385
